# non-temporal hint on the bf16 residual-stream copy written by the first norm and on the residual rows read by the norm passes
# speedup vs baseline: 1.0109x; 1.0009x over previous
; __device__ __forceinline__ unsigned cvt_pk_bf16(float lo, float hi) { unsigned r; asm volatile("v_cvt_pk_bf16_f32 %0, %1, %2" : "=v"(r) : "v"(lo), "v"(hi)); return r; }
; __device__ __forceinline__ float bf_lo(unsigned u) { return __uint_as_float(u << 16); }
; __device__ __forceinline__ float bf_hi(unsigned u) { return __uint_as_float(u & 0xffff0000u); }
; __global__ void __launch_bounds__(512, 2) fwd_kernel(const Args a) {
;     ...
;                     const bool lat = m < ML; const float* xr = lat ? xl + (size_t)m * D : xcs + (size_t)(m - ML) * D; const int vec = lat ? (m >> 13) : 2;
;                     const float* shp = ada + vec * 12288 + so; const float* scp = shp + 2048;
;                     f32x4 v[8]; float ss = 0.f;
;                     if (lat && lbf) { const u32x2* xq = (const u32x2*)(XBb + (size_t)m * D);
; #pragma unroll
;                         for (int j = 0; j < 8; ++j) { const u32x2 q = xq[64 * j + lane]; v[j] = (f32x4){bf_lo(q.x), bf_hi(q.x), bf_lo(q.y), bf_hi(q.y)}; }
;                     } else {
; #pragma unroll
;                         for (int j = 0; j < 8; ++j) v[j] = ((const f32x4*)xr)[64 * j + lane];
;                         if (lat) { u32x2* xw = (u32x2*)(XBb + (size_t)m * D);
; #pragma unroll
;                             for (int j = 0; j < 8; ++j) { u32x2 w; w.x = cvt_pk_bf16(v[j].x, v[j].y); w.y = cvt_pk_bf16(v[j].z, v[j].w); xw[64 * j + lane] = w; } }
.LBB0_446:
	s_andn2_b64 vcc, exec, s[34:35]
	v_lshlrev_b32_e32 v176, 4, v188
	s_cbranch_vccnz .LBB0_449
	v_readlane_b32 s64, v252, 18
	s_and_b64 s[34:35], s[0:1], exec
	v_readlane_b32 s65, v252, 19
	s_cselect_b32 s4, s21, s65
	s_cselect_b32 s14, s37, s64
	s_add_i32 s15, s40, 0xffffc000
	s_ashr_i32 s41, s40, 31
	s_and_b64 s[34:35], s[0:1], exec
	s_cselect_b32 s35, 0, s41
	s_cselect_b32 s34, s15, s40
	s_lshl_b64 s[34:35], s[34:35], 13
	s_add_u32 s34, s14, s34
	s_addc_u32 s35, s4, s35
	global_load_dwordx4 v[0:3], v176, s[34:35] nt
	global_load_dwordx4 v[4:7], v176, s[34:35] offset:1024 nt
	global_load_dwordx4 v[8:11], v176, s[34:35] offset:2048 nt
	global_load_dwordx4 v[12:15], v176, s[34:35] offset:3072 nt
	global_load_dwordx4 v[16:19], v107, s[34:35] nt
	global_load_dwordx4 v[20:23], v108, s[34:35] nt
	global_load_dwordx4 v[24:27], v109, s[34:35] nt
	global_load_dwordx4 v[28:31], v110, s[34:35] nt
	s_and_b64 vcc, exec, s[42:43]
	v_readlane_b32 s66, v252, 20
	v_readlane_b32 s67, v252, 21
	v_readlane_b32 s68, v252, 22
	v_readlane_b32 s69, v252, 23
	v_readlane_b32 s70, v252, 24
	v_readlane_b32 s71, v252, 25
	v_readlane_b32 s72, v252, 26
	v_readlane_b32 s73, v252, 27
	v_readlane_b32 s74, v252, 28
	v_readlane_b32 s75, v252, 29
	v_readlane_b32 s76, v252, 30
	v_readlane_b32 s77, v252, 31
	v_readlane_b32 s78, v252, 32
	v_readlane_b32 s79, v252, 33
	s_cbranch_vccz .LBB0_449
	s_lshl_b64 s[34:35], s[40:41], 12
	s_waitcnt vmcnt(0)
	v_cvt_pk_bf16_f32 v64, v0, v1
	v_cvt_pk_bf16_f32 v65, v2, v3
	v_lshl_add_u64 v[66:67], v[46:47], 0, s[34:35]
	global_store_dwordx2 v[66:67], v[64:65], off nt
	v_cvt_pk_bf16_f32 v64, v4, v5
	v_cvt_pk_bf16_f32 v65, v6, v7
	global_store_dwordx2 v[66:67], v[64:65], off offset:512 nt
	v_cvt_pk_bf16_f32 v64, v8, v9
	v_cvt_pk_bf16_f32 v65, v10, v11
	global_store_dwordx2 v[66:67], v[64:65], off offset:1024 nt
	v_cvt_pk_bf16_f32 v64, v12, v13
	v_cvt_pk_bf16_f32 v65, v14, v15
	global_store_dwordx2 v[66:67], v[64:65], off offset:1536 nt
	v_cvt_pk_bf16_f32 v64, v16, v17
	v_cvt_pk_bf16_f32 v65, v18, v19
	global_store_dwordx2 v[66:67], v[64:65], off offset:2048 nt
	v_cvt_pk_bf16_f32 v64, v20, v21
	v_cvt_pk_bf16_f32 v65, v22, v23
	global_store_dwordx2 v[66:67], v[64:65], off offset:2560 nt
	v_cvt_pk_bf16_f32 v64, v24, v25
	v_cvt_pk_bf16_f32 v65, v26, v27
	global_store_dwordx2 v[66:67], v[64:65], off offset:3072 nt
	v_cvt_pk_bf16_f32 v64, v28, v29
	v_cvt_pk_bf16_f32 v65, v30, v31
	global_store_dwordx2 v[66:67], v[64:65], off offset:3584 nt

; __device__ __forceinline__ float bf_lo(unsigned u) { return __uint_as_float(u << 16); }
; __device__ __forceinline__ float bf_hi(unsigned u) { return __uint_as_float(u & 0xffff0000u); }
; __global__ void __launch_bounds__(512, 2) fwd_kernel(const Args a) {
;     ...
;                     for (int m = m_beg; m < m_end; m += m_str) {
;                         const float* shp = ada + (m >> 13) * 12288 + so; const float* scp = shp + 2048;
;                         f32x4 v[8]; float ss = 0.f;
; #pragma unroll
;                         for (int j = 0; j < 8; ++j) { const u32x2 q = nq[j]; v[j] = (f32x4){bf_lo(q.x), bf_hi(q.x), bf_lo(q.y), bf_hi(q.y)}; }
;                         if (m + m_str < m_end) { const u32x2* xqn = (const u32x2*)(XBb + (size_t)(m + m_str) * D);
; #pragma unroll
;                             for (int j = 0; j < 8; ++j) nq[j] = xqn[64 * j + lane]; }
.Lfl_coef_ok:
	v_lshlrev_b32_e32 v14, 16, v46
	v_and_b32_e32 v15, 0xffff0000, v46
	v_lshlrev_b32_e32 v16, 16, v47
	v_and_b32_e32 v17, 0xffff0000, v47
	v_lshlrev_b32_e32 v18, 16, v44
	v_and_b32_e32 v19, 0xffff0000, v44
	v_lshlrev_b32_e32 v20, 16, v45
	v_and_b32_e32 v21, 0xffff0000, v45
	v_lshlrev_b32_e32 v22, 16, v42
	v_and_b32_e32 v23, 0xffff0000, v42
	v_lshlrev_b32_e32 v24, 16, v43
	v_and_b32_e32 v25, 0xffff0000, v43
	v_lshlrev_b32_e32 v26, 16, v40
	v_and_b32_e32 v27, 0xffff0000, v40
	v_lshlrev_b32_e32 v28, 16, v41
	v_and_b32_e32 v29, 0xffff0000, v41
	v_lshlrev_b32_e32 v48, 16, v38
	v_and_b32_e32 v49, 0xffff0000, v38
	v_lshlrev_b32_e32 v50, 16, v39
	v_and_b32_e32 v51, 0xffff0000, v39
	v_lshlrev_b32_e32 v52, 16, v36
	v_and_b32_e32 v53, 0xffff0000, v36
	v_lshlrev_b32_e32 v54, 16, v37
	v_and_b32_e32 v55, 0xffff0000, v37
	v_lshlrev_b32_e32 v56, 16, v34
	v_and_b32_e32 v57, 0xffff0000, v34
	v_lshlrev_b32_e32 v58, 16, v35
	v_and_b32_e32 v59, 0xffff0000, v35
	v_lshlrev_b32_e32 v60, 16, v66
	v_and_b32_e32 v61, 0xffff0000, v66
	v_lshlrev_b32_e32 v62, 16, v67
	v_and_b32_e32 v63, 0xffff0000, v67
	s_add_i32 s12, s10, s8
	s_cmp_ge_i32 s12, s2
	s_cbranch_scc1 .Lfl_nopf
	s_ashr_i32 s13, s12, 31
	s_lshl_b64 s[24:25], s[12:13], 12
	v_lshl_add_u64 v[82:83], v[2:3], 0, s[24:25]
	global_load_dwordx2 v[46:47], v[82:83], off nt
	global_load_dwordx2 v[44:45], v[82:83], off offset:512 nt
	global_load_dwordx2 v[42:43], v[82:83], off offset:1024 nt
	global_load_dwordx2 v[40:41], v[82:83], off offset:1536 nt
	global_load_dwordx2 v[38:39], v[82:83], off offset:2048 nt
	global_load_dwordx2 v[36:37], v[82:83], off offset:2560 nt
	global_load_dwordx2 v[34:35], v[82:83], off offset:3072 nt
	global_load_dwordx2 v[66:67], v[82:83], off offset:3584 nt
